# v2 + prologue: nt (streaming) hint on the one-time f32 input loads, gain loads of the weight transposes hoisted
# speedup vs baseline: 1.0104x; 1.0013x over previous
.LBB0_17:
	v_lshl_add_u64 v[44:45], v[34:35], 0, s[24:25]
	global_load_dwordx4 v[26:29], v[44:45], off offset:16 nt
	global_load_dwordx4 v[30:33], v[44:45], off nt
	s_add_u32 s38, s40, s12
	s_addc_u32 s39, s41, s13
	v_cmp_gt_i64_e32 vcc, s[38:39], v[40:41]
	v_cmp_lt_i64_e64 s[8:9], s[38:39], v[38:39]
	s_cbranch_vccnz .LBB0_19
	v_lshl_add_u64 v[2:3], v[34:35], 0, s[34:35]
	global_load_dwordx4 v[10:13], v[2:3], off offset:16 nt
	s_nop 0
	global_load_dwordx4 v[2:5], v[2:3], off nt
.LBB0_19:
	s_add_u32 s42, s10, s40
	s_addc_u32 s43, s11, s41
	v_cmp_gt_i64_e32 vcc, s[42:43], v[40:41]
	v_cmp_lt_i64_e64 s[4:5], s[42:43], v[38:39]
	s_cbranch_vccnz .LBB0_21
	v_lshl_add_u64 v[6:7], v[34:35], 0, s[30:31]
	global_load_dwordx4 v[18:21], v[6:7], off nt
	s_nop 0
	global_load_dwordx4 v[6:9], v[6:7], off offset:-16 nt
.LBB0_21:
	s_add_u32 s44, s19, s40
	s_addc_u32 s45, s15, s41
	v_cmp_gt_i64_e32 vcc, s[44:45], v[40:41]
	v_cmp_lt_i64_e64 s[6:7], s[44:45], v[38:39]
	s_cbranch_vccnz .LBB0_23
	v_lshl_add_u64 v[14:15], v[34:35], 0, s[36:37]
	global_load_dwordx4 v[22:25], v[14:15], off nt
	s_nop 0
	global_load_dwordx4 v[14:17], v[14:15], off offset:-16 nt

.LBB0_33:
	v_ashrrev_i64 v[20:21], 3, v[8:9]
	v_lshlrev_b64 v[12:13], 8, v[20:21]
	v_lshl_add_u64 v[22:23], v[4:5], 0, v[12:13]
	global_load_dwordx4 v[12:15], v[22:23], off nt
	global_load_dwordx4 v[16:19], v[22:23], off offset:128 nt
	v_ashrrev_i64 v[22:23], 15, v[8:9]
	v_and_b32_e32 v2, 0xfff, v20
	v_mad_u64_u32 v[20:21], s[28:29], v22, s10, v[2:3]
	v_mad_i32_i24 v11, v23, s10, v21
	v_mad_u64_u32 v[20:21], s[28:29], v20, s11, v[6:7]
	v_lshl_add_u64 v[8:9], v[8:9], 0, s[24:25]
	v_mov_b32_e32 v2, v21
	v_cmp_lt_i64_e32 vcc, s[8:9], v[8:9]
	v_mad_u64_u32 v[22:23], s[28:29], v11, s11, v[2:3]
	s_or_b64 s[6:7], vcc, s[6:7]
	v_mov_b32_e32 v21, v22
	s_waitcnt vmcnt(0)
	v_cvt_pk_bf16_f32 v12, v12, v16
	v_cvt_pk_bf16_f32 v13, v13, v17
	v_cvt_pk_bf16_f32 v14, v14, v18
	v_cvt_pk_bf16_f32 v15, v15, v19
	global_store_dwordx4 v[20:21], v[12:15], off offset:1024
	s_andn2_b64 exec, exec, s[6:7]
	s_cbranch_execnz .LBB0_33
	s_or_b64 exec, exec, s[6:7]

.LBB0_85:
	s_abs_i32 s5, s78
	s_mul_hi_u32 s6, s5, s74
	s_mul_i32 s36, s6, s69
	s_sub_i32 s5, s5, s36
	s_ashr_i32 s4, s78, 31
	s_add_i32 s36, s6, 1
	s_sub_i32 s37, s5, s69
	s_cmp_ge_u32 s5, s69
	s_cselect_b32 s6, s36, s6
	s_cselect_b32 s5, s37, s5
	s_add_i32 s36, s6, 1
	s_cmp_ge_u32 s5, s69
	s_cselect_b32 s5, s36, s6
	s_xor_b32 s5, s5, s4
	s_sub_i32 s80, s5, s4
	s_lshl_b32 s36, s80, 6
	s_mul_i32 s81, s73, s80
	v_or_b32_e32 v44, s36, v40
	s_add_i32 s79, s75, s81
	v_ashrrev_i32_e32 v45, 31, v44
	v_or_b32_e32 v4, 8, v44
	s_add_i32 s4, s79, 0x200
	v_mul_lo_u32 v6, v45, s68
	v_mad_u64_u32 v[2:3], s[38:39], v44, s68, 0
	v_mad_u64_u32 v[4:5], s[38:39], v4, s68, 0
	s_ashr_i32 s5, s4, 31
	v_add_u32_e32 v3, v3, v6
	v_add_u32_e32 v5, v5, v6
	v_lshl_add_u64 v[2:3], v[2:3], 2, s[8:9]
	s_lshl_b64 s[4:5], s[4:5], 2
	v_lshl_add_u64 v[4:5], v[4:5], 2, s[8:9]
	v_lshl_add_u64 v[2:3], v[2:3], 0, s[4:5]
	v_lshl_add_u64 v[4:5], v[4:5], 0, s[4:5]
	v_lshl_add_u64 v[2:3], v[2:3], 0, v[42:43]
	v_lshl_add_u64 v[4:5], v[4:5], 0, v[42:43]
	global_load_dwordx4 v[30:33], v[2:3], off nt
	global_load_dwordx4 v[26:29], v[4:5], off nt
	v_or_b32_e32 v2, 16, v44
	v_or_b32_e32 v4, 24, v44
	v_mad_u64_u32 v[2:3], s[38:39], v2, s68, 0
	v_mad_u64_u32 v[4:5], s[38:39], v4, s68, 0
	v_add_u32_e32 v3, v3, v6
	v_add_u32_e32 v5, v5, v6
	v_lshl_add_u64 v[2:3], v[2:3], 2, s[8:9]
	v_lshl_add_u64 v[4:5], v[4:5], 2, s[8:9]
	v_lshl_add_u64 v[2:3], v[2:3], 0, s[4:5]
	v_lshl_add_u64 v[4:5], v[4:5], 0, s[4:5]
	v_lshl_add_u64 v[2:3], v[2:3], 0, v[42:43]
	v_lshl_add_u64 v[4:5], v[4:5], 0, v[42:43]
	global_load_dwordx4 v[22:25], v[2:3], off nt
	global_load_dwordx4 v[18:21], v[4:5], off nt
	v_or_b32_e32 v2, 32, v44
	v_or_b32_e32 v4, 40, v44
	v_mad_u64_u32 v[2:3], s[38:39], v2, s68, 0
	v_mad_u64_u32 v[4:5], s[38:39], v4, s68, 0
	v_add_u32_e32 v3, v3, v6
	v_add_u32_e32 v5, v5, v6
	v_lshl_add_u64 v[2:3], v[2:3], 2, s[8:9]
	v_lshl_add_u64 v[4:5], v[4:5], 2, s[8:9]
	v_lshl_add_u64 v[2:3], v[2:3], 0, s[4:5]
	v_lshl_add_u64 v[4:5], v[4:5], 0, s[4:5]
	v_lshl_add_u64 v[2:3], v[2:3], 0, v[42:43]
	v_lshl_add_u64 v[4:5], v[4:5], 0, v[42:43]
	global_load_dwordx4 v[14:17], v[2:3], off nt
	global_load_dwordx4 v[10:13], v[4:5], off nt
	v_or_b32_e32 v2, 48, v44
	v_or_b32_e32 v4, 56, v44
	v_mad_u64_u32 v[2:3], s[38:39], v2, s68, 0
	v_mad_u64_u32 v[4:5], s[38:39], v4, s68, 0
	v_add_u32_e32 v3, v3, v6
	v_add_u32_e32 v5, v5, v6
	v_lshl_add_u64 v[2:3], v[2:3], 2, s[8:9]
	v_lshl_add_u64 v[4:5], v[4:5], 2, s[8:9]
	v_lshl_add_u64 v[2:3], v[2:3], 0, s[4:5]
	v_lshl_add_u64 v[4:5], v[4:5], 0, s[4:5]
	v_lshl_add_u64 v[2:3], v[2:3], 0, v[42:43]
	v_lshl_add_u64 v[4:5], v[4:5], 0, v[42:43]
	global_load_dwordx4 v[6:9], v[2:3], off nt
	s_nop 0
	global_load_dwordx4 v[2:5], v[4:5], off nt
	s_ashr_i32 s37, s36, 31
	v_mov_b32_e32 v62, 1.0
	v_mov_b32_e32 v64, 1.0
	v_mov_b32_e32 v66, 1.0
	v_mov_b32_e32 v68, 1.0
	v_mov_b32_e32 v70, 1.0
	v_mov_b32_e32 v72, 1.0
	v_mov_b32_e32 v74, 1.0
	v_mov_b32_e32 v76, 1.0
	s_andn2_b64 vcc, exec, s[34:35]
	s_cbranch_vccnz .Ltr_nogain
	v_lshl_add_u64 v[78:79], s[36:37], 0, v[40:41]
	v_lshl_add_u64 v[78:79], v[78:79], 2, s[10:11]
	global_load_dword v62, v[78:79], off
	global_load_dword v64, v[78:79], off offset:32
	global_load_dword v66, v[78:79], off offset:64
	global_load_dword v68, v[78:79], off offset:96
	global_load_dword v70, v[78:79], off offset:128
	global_load_dword v72, v[78:79], off offset:160
	global_load_dword v74, v[78:79], off offset:192
	global_load_dword v76, v[78:79], off offset:224

.LBB0_205:
	global_load_dwordx4 v[8:11], v[2:3], off offset:-16 nt
	global_load_dwordx4 v[12:15], v[2:3], off nt
	v_lshl_add_u64 v[6:7], v[6:7], 0, s[24:25]
	v_cmp_lt_i64_e32 vcc, s[28:29], v[6:7]
	v_lshl_add_u64 v[2:3], v[2:3], 0, s[6:7]
	s_or_b64 s[8:9], vcc, s[8:9]
	s_waitcnt vmcnt(1)
	v_cvt_pk_bf16_f32 v8, v8, v9
	v_cvt_pk_bf16_f32 v9, v10, v11
	s_waitcnt vmcnt(0)
	v_cvt_pk_bf16_f32 v10, v12, v13
	v_cvt_pk_bf16_f32 v11, v14, v15
	global_store_dwordx4 v[4:5], v[8:11], off
	v_lshl_add_u64 v[4:5], v[4:5], 0, s[10:11]
	s_andn2_b64 exec, exec, s[8:9]
	s_cbranch_execnz .LBB0_205
	s_or_b64 exec, exec, s[8:9]
	v_mov_b64_e32 v[2:3], s[24:25]

.LBB0_271:
	s_lshl_b64 s[24:25], s[20:21], 12
	s_waitcnt lgkmcnt(0)
	global_load_dwordx4 v[14:17], v34, s[6:7] nt
	v_lshl_add_u64 v[48:49], v[2:3], 0, s[24:25]
	s_waitcnt vmcnt(0)
	v_cvt_pk_bf16_f32 v18, v14, v15
	v_cvt_pk_bf16_f32 v19, v16, v17
	global_store_dwordx2 v[48:49], v[18:19], off
	global_load_dwordx4 v[18:21], v34, s[6:7] offset:1024 nt
	s_waitcnt vmcnt(0)
	v_cvt_pk_bf16_f32 v22, v18, v19
	v_cvt_pk_bf16_f32 v23, v20, v21
	global_store_dwordx2 v[48:49], v[22:23], off offset:512
	global_load_dwordx4 v[22:25], v34, s[6:7] offset:2048 nt
	s_waitcnt vmcnt(0)
	v_cvt_pk_bf16_f32 v26, v22, v23
	v_cvt_pk_bf16_f32 v27, v24, v25
	global_store_dwordx2 v[48:49], v[26:27], off offset:1024
	global_load_dwordx4 v[26:29], v34, s[6:7] offset:3072 nt
	v_lshl_add_u64 v[30:31], s[6:7], 0, v[34:35]
	v_add_co_u32_e64 v44, s[6:7], s22, v30
	s_waitcnt vmcnt(0)
	v_cvt_pk_bf16_f32 v30, v26, v27
	v_mul_f32_e32 v15, v15, v15
	v_addc_co_u32_e64 v45, s[6:7], 0, v31, s[6:7]
	v_cvt_pk_bf16_f32 v31, v28, v29
	global_store_dwordx2 v[48:49], v[30:31], off offset:1536
	global_load_dwordx4 v[30:33], v[44:45], off nt
	s_waitcnt vmcnt(0)
	v_cvt_pk_bf16_f32 v36, v30, v31
	v_cvt_pk_bf16_f32 v37, v32, v33
	global_store_dwordx2 v[48:49], v[36:37], off offset:2048
	global_load_dwordx4 v[36:39], v[44:45], off offset:1024 nt
	s_waitcnt vmcnt(0)
	v_cvt_pk_bf16_f32 v40, v36, v37
	v_cvt_pk_bf16_f32 v41, v38, v39
	global_store_dwordx2 v[48:49], v[40:41], off offset:2560
	global_load_dwordx4 v[40:43], v[44:45], off offset:2048 nt
	s_waitcnt vmcnt(0)
	v_cvt_pk_bf16_f32 v46, v40, v41
	v_cvt_pk_bf16_f32 v47, v42, v43
	global_store_dwordx2 v[48:49], v[46:47], off offset:3072
	global_load_dwordx4 v[44:47], v[44:45], off offset:3072 nt
	v_mul_f32_e32 v17, v17, v17
	v_fmac_f32_e32 v15, v14, v14
	v_fmac_f32_e32 v17, v16, v16
	v_add_f32_e32 v14, v15, v17
	v_mul_f32_e32 v15, v19, v19
	v_mul_f32_e32 v16, v21, v21
	v_fmac_f32_e32 v15, v18, v18
	v_fmac_f32_e32 v16, v20, v20
	v_add_f32_e32 v15, v15, v16
	v_add_f32_e32 v14, v14, v15
	v_mul_f32_e32 v15, v23, v23
	v_mul_f32_e32 v16, v25, v25
	v_fmac_f32_e32 v15, v22, v22
	v_fmac_f32_e32 v16, v24, v24
	v_add_f32_e32 v15, v15, v16
	v_add_f32_e32 v14, v14, v15
	v_mul_f32_e32 v15, v27, v27
	v_mul_f32_e32 v16, v29, v29
	v_fmac_f32_e32 v15, v26, v26
	v_fmac_f32_e32 v16, v28, v28
	v_add_f32_e32 v15, v15, v16
	v_add_f32_e32 v14, v14, v15
	v_cmp_lt_i32_e64 s[6:7], v7, v6
	v_mul_f32_e32 v15, v31, v31
	v_mul_f32_e32 v16, v33, v33
	v_fmac_f32_e32 v15, v30, v30
	v_fmac_f32_e32 v16, v32, v32
	v_add_f32_e32 v15, v15, v16
	v_add_f32_e32 v14, v14, v15
	v_mul_f32_e32 v15, v37, v37
	v_mul_f32_e32 v16, v39, v39
	v_fmac_f32_e32 v15, v36, v36
	v_fmac_f32_e32 v16, v38, v38
	v_add_f32_e32 v15, v15, v16
	v_add_f32_e32 v14, v14, v15
	v_mul_f32_e32 v15, v41, v41
	v_mul_f32_e32 v16, v43, v43
	v_fmac_f32_e32 v15, v40, v40
	v_fmac_f32_e32 v16, v42, v42
	v_add_f32_e32 v15, v15, v16
	v_add_f32_e32 v14, v14, v15
	s_waitcnt vmcnt(0)
	v_mul_f32_e32 v15, v45, v45
	v_mul_f32_e32 v16, v47, v47
	v_fmac_f32_e32 v15, v44, v44
	v_fmac_f32_e32 v16, v46, v46
	v_cndmask_b32_e64 v13, v1, v7, s[6:7]
	v_add_f32_e32 v15, v15, v16
	v_lshlrev_b32_e32 v13, 2, v13
	v_add_f32_e32 v14, v14, v15
	ds_bpermute_b32 v13, v13, v14
	v_cmp_lt_i32_e64 s[6:7], v8, v6
	v_cvt_pk_bf16_f32 v16, v44, v45
	v_cvt_pk_bf16_f32 v17, v46, v47
	global_store_dwordx2 v[48:49], v[16:17], off offset:3584
	s_waitcnt lgkmcnt(0)
	v_add_f32_e32 v13, v14, v13
	v_cndmask_b32_e64 v15, v1, v8, s[6:7]
	v_lshlrev_b32_e32 v15, 2, v15
	ds_bpermute_b32 v14, v15, v13
	v_cmp_lt_i32_e64 s[6:7], v9, v6
	s_waitcnt lgkmcnt(0)
	v_add_f32_e32 v13, v13, v14
	v_cndmask_b32_e64 v15, v1, v9, s[6:7]
	v_lshlrev_b32_e32 v15, 2, v15
	ds_bpermute_b32 v14, v15, v13
	v_cmp_lt_i32_e64 s[6:7], v10, v6
	s_waitcnt lgkmcnt(0)
	v_add_f32_e32 v13, v13, v14
	v_cndmask_b32_e64 v15, v1, v10, s[6:7]
	v_lshlrev_b32_e32 v15, 2, v15
	ds_bpermute_b32 v14, v15, v13
	v_cmp_lt_i32_e64 s[6:7], v11, v6
	s_waitcnt lgkmcnt(0)
	v_add_f32_e32 v13, v13, v14
	v_cndmask_b32_e64 v15, v1, v11, s[6:7]
	v_lshlrev_b32_e32 v15, 2, v15
	ds_bpermute_b32 v14, v15, v13
	v_cmp_lt_i32_e64 s[6:7], v12, v6
	s_waitcnt lgkmcnt(0)
	v_add_f32_e32 v13, v13, v14
	v_cndmask_b32_e64 v15, v1, v12, s[6:7]
	v_lshlrev_b32_e32 v14, 2, v15
	ds_bpermute_b32 v14, v14, v13
	s_and_saveexec_b64 s[6:7], vcc
	s_cbranch_execz .LBB0_268
	s_lshl_b64 s[20:21], s[20:21], 7
	s_waitcnt lgkmcnt(0)
	v_add_f32_e32 v13, v13, v14
	v_lshl_add_u64 v[16:17], v[4:5], 0, s[20:21]
	v_cndmask_b32_e64 v13, 0, v13, s[4:5]
	global_store_dword v[16:17], v13, off
	s_branch .LBB0_268
